# v048 stack + static s_setprio 1 for waves 4-7 in MLA loop + raw bf16 tile-store fast path for G1A/G4 epilogues
# speedup vs baseline: 1.0079x; 1.0008x over previous
; #define opqp(x) ((x) + opqz())
; #define LDS_BAR() do { asm volatile("s_waitcnt lgkmcnt(0)" ::: "memory"); __builtin_amdgcn_s_barrier(); asm volatile("" ::: "memory"); } while (0)
; DEVI void gemm256(const P& p, const u16* A, int lda, const u16* Bt, int ldb, int K, int brow, int bcol, int mode,
;                         int aux, int layer, int bmode) {
;     ...
;   char* ws = opqp(p.ws);
;   const int bb = brow / TPB;
;   const int trow = brow - bb * TPB;
;   u16* stg = (u16*)shm;
;   const int tid = TIDX;
;     ...
; #pragma unroll
;   for (int ai = 0; ai < 2; ++ai)
; #pragma unroll
;     for (int bj = 0; bj < (G8 ? 2 : 1); ++bj)
; #pragma unroll
;       for (int m = 0; m < 4; ++m)
; #pragma unroll
;         for (int n = 0; n < 2; ++n) {
;           const int R = ai * HALF + wr * 64 + m * 16 + fr;
;           const int chunk = bj * 16 + wc * 4 + n * 2 + (fq >> 1);
;           f32x4 v = acc[ai][bj][m][n];
;           uint2 pk = make_uint2(pk2(v[0], v[1]), pk2(v[2], v[3]));
;           *(uint2*)(stg + R * 256 + SWZ(R, chunk) * 8 + (fq & 1) * 4) = pk;
;         }
;   LDS_BAR();
.LBB0_195:
	s_or_b64 exec, exec, s[2:3]
	v_lshrrev_b32_e32 v134, 1, v134
	v_lshlrev_b32_e32 v133, 3, v133
	v_lshlrev_b32_e32 v136, 4, v134
	v_and_b32_e32 v133, 8, v133
	v_or_b32_e32 v134, v134, v135
	v_add_u32_e32 v133, 16, v133
	v_lshlrev_b32_e32 v132, 15, v132
	v_lshlrev_b32_e32 v135, 9, v131
	v_cvt_pk_bf16_f32 v126, v126, v127
	v_cvt_pk_bf16_f32 v127, v128, v129
	v_bitop3_b32 v128, v136, v134, v131 bitop3:0x36
	v_add3_u32 v132, v133, v132, v135
	v_lshlrev_b32_e32 v128, 4, v128
	v_cvt_pk_bf16_f32 v90, v90, v91
	v_cvt_pk_bf16_f32 v91, v92, v93
	v_or_b32_e32 v92, 16, v134
	s_mov_b64 s[28:29], 0
	v_add_u32_e32 v129, v132, v128
	v_cvt_pk_bf16_f32 v110, v110, v111
	v_cvt_pk_bf16_f32 v111, v112, v113
	v_cvt_pk_bf16_f32 v98, v98, v99
	v_cvt_pk_bf16_f32 v99, v100, v101
	v_bitop3_b32 v92, v136, v92, v131 bitop3:0x36
	v_or_b32_e32 v100, 18, v134
	s_waitcnt vmcnt(0)
	ds_write2st64_b64 v129, v[110:111], v[98:99] offset0:32 offset1:48
	v_lshlrev_b32_e32 v98, 4, v92
	v_cvt_pk_bf16_f32 v92, v94, v95
	v_bitop3_b32 v94, v136, v100, v131 bitop3:0x36
	v_or_b32_e32 v133, 2, v134
	v_lshlrev_b32_e32 v94, 4, v94
	v_cvt_pk_bf16_f32 v122, v122, v123
	v_cvt_pk_bf16_f32 v123, v124, v125
	v_bitop3_b32 v124, v136, v133, v131 bitop3:0x36
	v_add_u32_e32 v95, v132, v94
	v_cvt_pk_bf16_f32 v66, v66, v67
	v_cvt_pk_bf16_f32 v67, v68, v69
	v_cvt_pk_bf16_f32 v54, v54, v55
	v_cvt_pk_bf16_f32 v55, v56, v57
	v_add_u32_e32 v56, 0x10000, v132
	v_lshlrev_b32_e32 v124, 4, v124
	ds_write2st64_b64 v95, v[66:67], v[54:55] offset0:32 offset1:48
	v_cvt_pk_bf16_f32 v54, v78, v79
	v_cvt_pk_bf16_f32 v55, v80, v81
	v_add_u32_e32 v57, v56, v128
	ds_write_b64 v57, v[54:55]
	v_cvt_pk_bf16_f32 v54, v70, v71
	v_cvt_pk_bf16_f32 v55, v72, v73
	v_add_u32_e32 v57, v56, v124
	ds_write_b64 v57, v[54:55]
	v_add_u32_e32 v57, 0x12000, v132
	v_cvt_pk_bf16_f32 v50, v50, v51
	v_cvt_pk_bf16_f32 v51, v52, v53
	v_add_u32_e32 v52, v57, v124
	ds_write_b64 v52, v[50:51]
	v_add_u32_e32 v50, 0x14000, v132
	v_cvt_pk_bf16_f32 v42, v42, v43
	v_cvt_pk_bf16_f32 v43, v44, v45
	v_add_u32_e32 v44, v50, v124
	v_add_u32_e32 v125, v132, v124
	v_cvt_pk_bf16_f32 v102, v102, v103
	v_cvt_pk_bf16_f32 v103, v104, v105
	ds_write_b64 v44, v[42:43]
	v_add_u32_e32 v42, 0x16000, v132
	v_cvt_pk_bf16_f32 v118, v118, v119
	v_cvt_pk_bf16_f32 v119, v120, v121
	v_cvt_pk_bf16_f32 v114, v114, v115
	v_cvt_pk_bf16_f32 v115, v116, v117
	ds_write2st64_b64 v125, v[102:103], v[90:91] offset0:32 offset1:48
	v_cvt_pk_bf16_f32 v90, v106, v107
	v_cvt_pk_bf16_f32 v91, v108, v109
	v_add_u32_e32 v99, v132, v98
	v_cvt_pk_bf16_f32 v93, v96, v97
	v_cvt_pk_bf16_f32 v86, v86, v87
	v_cvt_pk_bf16_f32 v87, v88, v89
	v_cvt_pk_bf16_f32 v82, v82, v83
	v_cvt_pk_bf16_f32 v83, v84, v85
	v_cvt_pk_bf16_f32 v74, v74, v75
	v_cvt_pk_bf16_f32 v75, v76, v77
	v_cvt_pk_bf16_f32 v62, v62, v63
	v_cvt_pk_bf16_f32 v63, v64, v65
	v_cvt_pk_bf16_f32 v54, v58, v59
	v_cvt_pk_bf16_f32 v55, v60, v61
	v_add_u32_e32 v58, v57, v128
	v_cvt_pk_bf16_f32 v46, v46, v47
	v_cvt_pk_bf16_f32 v47, v48, v49
	v_add_u32_e32 v48, v50, v128
	v_cvt_pk_bf16_f32 v38, v38, v39
	v_cvt_pk_bf16_f32 v39, v40, v41
	v_add_u32_e32 v40, v42, v128
	v_cvt_pk_bf16_f32 v34, v34, v35
	v_cvt_pk_bf16_f32 v35, v36, v37
	v_add_u32_e32 v36, v42, v124
	v_cvt_pk_bf16_f32 v30, v30, v31
	v_cvt_pk_bf16_f32 v31, v32, v33
	v_add_u32_e32 v32, v56, v98
	v_cvt_pk_bf16_f32 v26, v26, v27
	v_cvt_pk_bf16_f32 v27, v28, v29
	v_add_u32_e32 v28, v56, v94
	v_cvt_pk_bf16_f32 v22, v22, v23
	v_cvt_pk_bf16_f32 v23, v24, v25
	v_add_u32_e32 v24, v57, v98
	v_cvt_pk_bf16_f32 v18, v18, v19
	v_cvt_pk_bf16_f32 v19, v20, v21
	v_add_u32_e32 v20, v57, v94
	v_cvt_pk_bf16_f32 v14, v14, v15
	v_cvt_pk_bf16_f32 v15, v16, v17
	v_add_u32_e32 v16, v50, v98
	v_cvt_pk_bf16_f32 v10, v10, v11
	v_cvt_pk_bf16_f32 v11, v12, v13
	v_add_u32_e32 v12, v50, v94
	v_cvt_pk_bf16_f32 v6, v6, v7
	v_cvt_pk_bf16_f32 v7, v8, v9
	v_add_u32_e32 v8, v42, v98
	v_cvt_pk_bf16_f32 v2, v2, v3
	v_cvt_pk_bf16_f32 v3, v4, v5
	v_add_u32_e32 v4, v42, v94
	ds_write2st64_b64 v129, v[126:127], v[118:119] offset1:16
	ds_write2st64_b64 v125, v[122:123], v[114:115] offset1:16
	ds_write2st64_b64 v99, v[90:91], v[86:87] offset1:16
	ds_write2st64_b64 v95, v[92:93], v[82:83] offset1:16
	ds_write2st64_b64 v99, v[74:75], v[62:63] offset0:32 offset1:48
	ds_write_b64 v58, v[54:55]
	ds_write_b64 v48, v[46:47]
	ds_write_b64 v40, v[38:39]
	ds_write_b64 v36, v[34:35]
	ds_write_b64 v32, v[30:31]
	ds_write_b64 v28, v[26:27]
	ds_write_b64 v24, v[22:23]
	ds_write_b64 v20, v[18:19]
	ds_write_b64 v16, v[14:15]
	ds_write_b64 v12, v[10:11]
	ds_write_b64 v8, v[6:7]
	ds_write_b64 v4, v[2:3]
	s_waitcnt lgkmcnt(0)
	s_barrier
	s_mov_b64 s[2:3], -1
	s_and_b64 vcc, exec, s[36:37]
	v_and_b32_e32 v64, 16, v0
	v_readlane_b32 s26, v251, 10
	s_cbranch_vccz .LBB0_313
; DEVI void gemm256(const P& p, const u16* A, int lda, const u16* Bt, int ldb, int K, int brow, int bcol, int mode,
;                         int aux, int layer, int bmode) {
;     ...
;   } else {
;     bool tr0 = false, tr1 = false;
;     if (mode == M_G1A) { tr0 = bcol >= C_AV && bcol < C_AG; tr1 = bcol + HALF >= C_AV && bcol + HALF < C_AG; }
;     else if (mode == M_G3) { tr1 = true; }
; #pragma unroll 4
;     for (int it = 0; it < 16; ++it) {
;       const int R = it * 16 + (tid >> 5), c = tid & 31;
;       if ((c < 16) ? tr0 : tr1) continue;
;       const int row = brow + R, col = bcol + c * 8;
;       bf16x8 raw = *(const bf16x8*)(stg + R * 256 + SWZ(R, c) * 8);
;       if (mode == M_G1A) {
;         *(bf16x8*)((u16*)(ws + O_PROJ) + (size_t)row * NP + col) = raw;
;       } else if (mode == M_G4) {
;         *(bf16x8*)((u16*)(ws + O_YBR) + (size_t)row * 8192 + aux * 2048 + col) = raw;
;       } else {
	v_readlane_b32 s60, v249, 42
	v_readlane_b32 s64, v249, 46
	v_readlane_b32 s2, v249, 53
	s_mul_i32 s47, s72, 0xffffef00
	v_readlane_b32 s65, v249, 47
	s_add_u32 s80, s64, s28
	s_addc_u32 s81, s65, s29
	s_add_i32 s46, s47, s70
	s_and_b32 s2, s97, 0xfffffe00
	v_readlane_b32 s3, v249, 54
	s_cmpk_eq_i32 s2, 0x400
	s_cselect_b64 s[2:3], -1, 0
	s_add_i32 s5, s97, 0xfffffc80
	s_cmpk_lt_u32 s5, 0x200
	s_cselect_b64 s[6:7], -1, 0
	v_cndmask_b32_e64 v0, 0, 1, s[6:7]
	v_cndmask_b32_e64 v2, 0, 1, s[68:69]
	v_and_b32_e32 v3, 31, v130
	s_and_b64 s[2:3], s[38:39], s[2:3]
	v_cndmask_b32_e64 v0, v2, v0, s[38:39]
	v_cndmask_b32_e64 v65, 0, 1, s[2:3]
	v_cmp_gt_u32_e32 vcc, 16, v3
	v_and_b32_e32 v2, 1, v0
	v_ashrrev_i32_e32 v10, 5, v130
	v_cndmask_b32_e32 v0, v0, v65, vcc
	v_and_b32_e32 v0, 1, v0
	v_cmp_eq_u32_e32 vcc, 1, v0
	v_and_b32_e32 v0, 15, v10
	v_cmp_eq_u32_e64 s[44:45], 1, v2
	v_lshl_add_u32 v2, v3, 3, s97
	v_bitop3_b32 v0, v0, v3, v64 bitop3:0x36
	v_lshlrev_b32_e32 v8, 4, v0
	v_readlane_b32 s2, v248, 15
	v_ashrrev_i32_e32 v0, 8, v2
	s_xor_b64 s[82:83], vcc, -1
	v_add_u32_e32 v4, s2, v2
	v_lshl_add_u32 v0, s72, 2, v0
	s_movk_i32 s2, 0x1100
	s_mov_b64 s[88:89], s[84:85]
	v_mad_i64_i32 v[12:13], s[2:3], v0, s2, 0
	v_and_b32_e32 v0, 0xf8, v2
	s_add_u32 s84, s80, 0x2221a000
	v_ashrrev_i32_e32 v3, 31, v2
	v_lshlrev_b32_e32 v0, 1, v0
	s_addc_u32 s85, s81, 0
	v_lshl_add_u64 v[6:7], s[80:81], 0, v[0:1]
	s_mov_b64 s[2:3], 0x1b28a000
	v_lshlrev_b64 v[16:17], 1, v[2:3]
	s_cmp_lg_u32 s46, 0
	v_lshl_add_u64 v[14:15], v[6:7], 0, s[2:3]
	v_lshl_add_u64 v[6:7], s[80:81], 0, v[16:17]
	s_mov_b64 s[2:3], 0x1990a000
	s_cselect_b64 s[54:55], -1, 0
	s_ashr_i32 s73, s72, 31
	s_add_i32 s5, s46, 0xffffff00
	v_lshl_add_u64 v[18:19], v[6:7], 0, s[2:3]
	s_lshl_b64 s[2:3], s[72:73], 12
	s_ashr_i32 s6, s5, 31
	s_add_u32 s56, s2, s5
	v_readlane_b32 s2, v248, 16
	s_addc_u32 s57, s3, s6
	s_add_i32 s2, s2, s72
	s_mul_hi_i32 s3, s2, 0x6000
	s_mulk_i32 s2, 0x6000
	s_add_u32 s2, s80, s2
	s_addc_u32 s3, s81, s3
	s_add_u32 s58, s2, 0x5614000
	s_addc_u32 s59, s3, 0
	s_lshl_b64 s[2:3], s[72:73], 19
	v_writelane_b32 v248, s2, 20
	v_lshlrev_b64 v[20:21], 2, v[2:3]
	v_lshl_add_u64 v[2:3], s[80:81], 0, v[20:21]
	v_writelane_b32 v248, s3, 21
	s_mov_b64 s[2:3], 0x568a000
	v_lshl_add_u64 v[22:23], v[2:3], 0, s[2:3]
	v_readlane_b32 s2, v248, 17
	s_add_u32 s2, s80, s2
	s_addc_u32 s3, s81, 0
	v_readlane_b32 s61, v249, 43
	s_add_u32 s60, s2, 0x562c000
	s_addc_u32 s61, s3, 0
	s_add_u32 s2, s80, 0xa28a000
	v_readlane_b32 s8, v251, 11
	s_addc_u32 s3, s81, 0
	s_lshl_b64 s[6:7], s[34:35], 1
	v_ashrrev_i32_e32 v5, 31, v4
	v_readlane_b32 s9, v251, 12
	v_readlane_b32 s10, v251, 13
	v_readlane_b32 s11, v251, 14
	v_readlane_b32 s12, v251, 15
	v_readlane_b32 s13, v251, 16
	v_readlane_b32 s14, v251, 17
	v_readlane_b32 s15, v251, 18
	v_readlane_b32 s16, v251, 19
	v_readlane_b32 s17, v251, 20
	v_readlane_b32 s18, v251, 21
	v_readlane_b32 s19, v251, 22
	v_readlane_b32 s20, v251, 23
	v_readlane_b32 s21, v251, 24
	v_readlane_b32 s22, v251, 25
	v_readlane_b32 s23, v251, 26
	s_add_u32 s6, s2, s6
	v_lshl_add_u64 v[30:31], v[4:5], 2, s[12:13]
	v_readlane_b32 s8, v249, 26
	s_addc_u32 s7, s3, s7
	v_lshl_add_u64 v[26:27], s[2:3], 0, v[16:17]
	s_lshl_b64 s[2:3], s[72:73], 21
	v_readlane_b32 s12, v249, 30
	v_lshl_add_u64 v[24:25], s[6:7], 0, v[16:17]
	v_readlane_b32 s13, v249, 31
	s_add_u32 s6, s12, s2
	s_addc_u32 s7, s13, s3
	v_ashrrev_i32_e32 v11, 31, v10
	s_add_u32 s2, s28, s2
	v_lshlrev_b64 v[2:3], 13, v[10:11]
	s_addc_u32 s3, s29, s3
	v_lshl_add_u64 v[32:33], s[6:7], 0, v[2:3]
	v_lshl_add_u64 v[2:3], s[2:3], 0, v[2:3]
	v_lshl_add_u64 v[2:3], v[2:3], 0, v[20:21]
	v_lshl_add_u64 v[34:35], s[64:65], 0, v[2:3]
	v_lshl_add_u64 v[2:3], s[56:57], 0, v[10:11]
	v_readlane_b32 s9, v249, 27
	v_lshlrev_b64 v[2:3], 13, v[2:3]
	v_readlane_b32 s62, v249, 44
	v_readlane_b32 s63, v249, 45
	v_readlane_b32 s66, v249, 48
	v_readlane_b32 s67, v249, 49
	v_readlane_b32 s20, v249, 38
	v_lshl_or_b32 v0, v10, 9, v8
	v_lshl_add_u64 v[40:41], s[8:9], 0, v[2:3]
	v_lshl_add_u64 v[2:3], v[2:3], 0, v[20:21]
	s_mov_b32 s50, 0
	v_lshl_add_u64 v[28:29], s[62:63], 0, v[20:21]
	v_add_u32_e32 v36, s70, v10
	v_add_u32_e32 v0, 16, v0
	v_lshl_add_u32 v38, v10, 1, s4
	v_lshl_add_u64 v[42:43], s[62:63], 0, v[2:3]
	s_mov_b64 s[66:67], 0
	s_movk_i32 s20, 0x600
	v_readlane_b32 s10, v249, 28
	v_readlane_b32 s11, v249, 29
	v_readlane_b32 s14, v249, 32
	v_readlane_b32 s15, v249, 33
	v_readlane_b32 s16, v249, 34
	v_readlane_b32 s17, v249, 35
	v_readlane_b32 s18, v249, 36
	v_readlane_b32 s19, v249, 37
	v_readlane_b32 s21, v249, 39
	v_readlane_b32 s22, v249, 40
	v_readlane_b32 s23, v249, 41
	s_cmp_eq_u32 s71, 6
	s_cbranch_scc1 .Lg5_disp
	s_cmp_eq_u32 s71, 4
	s_cbranch_scc1 .Lraw_g4
	s_cmp_lg_u32 s71, 0
	s_cbranch_scc1 .LBB0_198
	s_cmp_eq_u64 s[82:83], exec
	s_cbranch_scc0 .LBB0_198
	s_movk_i32 s2, 0x3a00
	v_mad_i64_i32 v[52:53], s[2:3], v36, s2, v[26:27]
	s_mov_b64 s[4:5], 0x3a000
	s_branch .Lraw_go
; DEVI void gemm256(const P& p, const u16* A, int lda, const u16* Bt, int ldb, int K, int brow, int bcol, int mode,
;                         int aux, int layer, int bmode) {
;     ...
; #pragma unroll 4
;     for (int it = 0; it < 16; ++it) {
;       const int R = it * 16 + (tid >> 5), c = tid & 31;
;       if ((c < 16) ? tr0 : tr1) continue;
;       const int row = brow + R, col = bcol + c * 8;
;       bf16x8 raw = *(const bf16x8*)(stg + R * 256 + SWZ(R, c) * 8);
;       if (mode == M_G1A) {
;         *(bf16x8*)((u16*)(ws + O_PROJ) + (size_t)row * NP + col) = raw;
;       } else if (mode == M_G4) {
;         *(bf16x8*)((u16*)(ws + O_YBR) + (size_t)row * 8192 + aux * 2048 + col) = raw;
.Lraw_g4:
	v_ashrrev_i32_e32 v37, 31, v36
	v_lshlrev_b64 v[52:53], 14, v[36:37]
	v_lshl_add_u64 v[52:53], v[24:25], 0, v[52:53]
	s_mov_b64 s[4:5], 0x40000
.Lraw_go:
	v_add_u32_e32 v168, 0x10000, v0
	ds_read_b128 v[66:69], v0
	ds_read_b128 v[70:73], v0 offset:8192
	ds_read_b128 v[74:77], v0 offset:16384
	ds_read_b128 v[78:81], v0 offset:24576
	ds_read_b128 v[82:85], v0 offset:32768
	ds_read_b128 v[86:89], v0 offset:40960
	ds_read_b128 v[90:93], v0 offset:49152
	ds_read_b128 v[94:97], v0 offset:57344
	ds_read_b128 v[98:101], v168
	ds_read_b128 v[102:105], v168 offset:8192
	ds_read_b128 v[106:109], v168 offset:16384
	ds_read_b128 v[110:113], v168 offset:24576
	ds_read_b128 v[114:117], v168 offset:32768
	ds_read_b128 v[118:121], v168 offset:40960
	ds_read_b128 v[122:125], v168 offset:49152
	ds_read_b128 v[126:129], v168 offset:57344
	s_waitcnt lgkmcnt(15)
	global_store_dwordx4 v[52:53], v[66:69], off
	v_lshl_add_u64 v[52:53], v[52:53], 0, s[4:5]
	s_waitcnt lgkmcnt(14)
	global_store_dwordx4 v[52:53], v[70:73], off
	v_lshl_add_u64 v[52:53], v[52:53], 0, s[4:5]
	s_waitcnt lgkmcnt(13)
	global_store_dwordx4 v[52:53], v[74:77], off
	v_lshl_add_u64 v[52:53], v[52:53], 0, s[4:5]
	s_waitcnt lgkmcnt(12)
	global_store_dwordx4 v[52:53], v[78:81], off
	v_lshl_add_u64 v[52:53], v[52:53], 0, s[4:5]
	s_waitcnt lgkmcnt(11)
	global_store_dwordx4 v[52:53], v[82:85], off
	v_lshl_add_u64 v[52:53], v[52:53], 0, s[4:5]
	s_waitcnt lgkmcnt(10)
	global_store_dwordx4 v[52:53], v[86:89], off
	v_lshl_add_u64 v[52:53], v[52:53], 0, s[4:5]
	s_waitcnt lgkmcnt(9)
	global_store_dwordx4 v[52:53], v[90:93], off
	v_lshl_add_u64 v[52:53], v[52:53], 0, s[4:5]
	s_waitcnt lgkmcnt(8)
	global_store_dwordx4 v[52:53], v[94:97], off
	v_lshl_add_u64 v[52:53], v[52:53], 0, s[4:5]
	s_waitcnt lgkmcnt(7)
	global_store_dwordx4 v[52:53], v[98:101], off
	v_lshl_add_u64 v[52:53], v[52:53], 0, s[4:5]
	s_waitcnt lgkmcnt(6)
	global_store_dwordx4 v[52:53], v[102:105], off
	v_lshl_add_u64 v[52:53], v[52:53], 0, s[4:5]
	s_waitcnt lgkmcnt(5)
	global_store_dwordx4 v[52:53], v[106:109], off
	v_lshl_add_u64 v[52:53], v[52:53], 0, s[4:5]
	s_waitcnt lgkmcnt(4)
	global_store_dwordx4 v[52:53], v[110:113], off
	v_lshl_add_u64 v[52:53], v[52:53], 0, s[4:5]
	s_waitcnt lgkmcnt(3)
	global_store_dwordx4 v[52:53], v[114:117], off
	v_lshl_add_u64 v[52:53], v[52:53], 0, s[4:5]
	s_waitcnt lgkmcnt(2)
	global_store_dwordx4 v[52:53], v[118:121], off
	v_lshl_add_u64 v[52:53], v[52:53], 0, s[4:5]
	s_waitcnt lgkmcnt(1)
	global_store_dwordx4 v[52:53], v[122:125], off
	v_lshl_add_u64 v[52:53], v[52:53], 0, s[4:5]
	s_waitcnt lgkmcnt(0)
	global_store_dwordx4 v[52:53], v[126:129], off
	s_branch .LBB0_305
.Lg5_disp:
	s_cmp_lg_u32 s98, 0
	s_cbranch_scc1 .Lg5_half
	s_mov_b64 s[4:5], 0x20000
	s_and_b64 vcc, exec, s[54:55]
	s_cbranch_vccz .Lg5_ctx
	v_lshl_add_u64 v[52:53], v[40:41], 0, v[20:21]
	v_mov_b32_e32 v54, v42
	v_mov_b32_e32 v55, v43
	s_mov_b64 s[2:3], s[58:59]
	s_branch .Lg5_common
